# merge start delay lengthened to ~10us
# baseline (speedup 1.0000x reference)
; __global__ void __launch_bounds__(NTHREADS, 2) fwd_kernel(Args A) {
;     ...
;         case 4: if (PMASK & 16) { pg8::Gemm g{(const bf16_t*)(ws + WS_Y), wl + WT_BR, Mx, DM, DM, 0, 0}; const bool coop = (ph_hi - ph_lo > 1);
;                   if (last) S.init(NLAT, DM, C.G, C.bid); else if (coop) S.init(NLAT, DM, C.G, C.bid, NCTX, 4); else S.init(MROWS, DM, C.G, C.bid);
;                   pg8::EpiMerge E{(const bf16_t*)(ws + WS_G), (bf16_t*)(ws + WS_MB), (float*)(ws + WS_PB)};
;                   pg8::gemm_phase<pg8::EpiMerge, true>(C.lds, C.tid, g, S, E);
.LBB0_242:
	v_readlane_b32 s100, v249, 56
	s_nop 3
	s_bitcmp1_b32 s100, 3
	s_cbranch_scc0 .Lmerge_nodelay
	s_sleep 127
	s_sleep 127
	s_sleep 60
